# lane-transpose (ds_bpermute) before A/D epilogue stores so 4 adjacent lanes write one 64B segment
# speedup vs baseline: 1.0167x; 1.0167x over previous
; __device__ __forceinline__ unsigned cvt_pk_bf16(float lo, float hi) { unsigned r; asm volatile("v_cvt_pk_bf16_f32 %0, %1, %2" : "=v"(r) : "v"(lo), "v"(hi)); return r; }
;     __device__ __forceinline__ void operator()(const f32x4 (&acc)[2][2][4][2], const Unit& u, int wr, int wc, int fr, int fq) const {
;         asm volatile("" : "+v"(fr), "+v"(fq));
;         const int rl0 = wr * 64 + fr, col0 = u.pn * BM + wc * 32 + 8 * fq;
; #pragma unroll
;         for (int ai = 0; ai < 2; ++ai)
; #pragma unroll
;             for (int m = 0; m < 4; ++m) { const int rl = rl0 + ai * HALF + m * 16; bf16_t* rowp = O + (size_t)(u.pm * BM + rl) * ldc + col0;
;                 const float s = rst[u.idx * BM + rl];
; #pragma unroll
;                 for (int bj = 0; bj < 2; ++bj) { f32x4 v0 = acc[ai][bj][m][0] * s, v1 = acc[ai][bj][m][1] * s;
;                     if (ACT == 1) {
; #pragma unroll
;                         for (int e = 0; e < 4; ++e) { const float a = fmaxf(v0[e], 0.f), b = fmaxf(v1[e], 0.f); v0[e] = a * a; v1[e] = b * b; } }
;                     u32x4 w; w.x = cvt_pk_bf16(v0[0], v0[1]); w.y = cvt_pk_bf16(v0[2], v0[3]); w.z = cvt_pk_bf16(v1[0], v1[1]); w.w = cvt_pk_bf16(v1[2], v1[3]);
;                     __builtin_nontemporal_store(w, (u32x4*)(rowp + bj * HALF)); } }
;     }
.LBB0_194:
	v_mbcnt_lo_u32_b32 v246, -1, 0
	v_mbcnt_hi_u32_b32 v246, -1, v246
	v_and_b32_e32 v249, 3, v246
	v_lshrrev_b32_e32 v246, 2, v246
	v_lshl_add_u32 v246, v249, 4, v246
	v_lshlrev_b32_e32 v246, 2, v246
	s_lshl_b32 s41, s78, 8
	v_mov_b32_e32 v142, v131
	v_mov_b32_e32 v143, v146
	s_or_b32 s41, s41, s68
	s_andn2_b64 vcc, exec, s[44:45]
	v_lshl_add_u32 v144, v143, 3, s41
	s_lshl_b32 s41, s76, 10
	v_add_u32_e32 v149, s65, v142
	s_add_i32 s41, s41, 0
	v_lshl_add_u32 v142, s77, 8, v149
	v_lshl_add_u32 v149, v149, 2, s41
	v_add_u32_e32 v149, 0x20000, v149
	ds_read_b32 v150, v149
	v_ashrrev_i32_e32 v143, 31, v142
	v_ashrrev_i32_e32 v145, 31, v144
	v_lshlrev_b64 v[152:153], 12, v[142:143]
	v_lshl_add_u64 v[152:153], s[36:37], 0, v[152:153]
	v_lshlrev_b64 v[144:145], 1, v[144:145]
	v_lshl_add_u64 v[152:153], v[152:153], 0, v[144:145]
	s_waitcnt lgkmcnt(0)
	v_pk_mul_f32 v[128:129], v[128:129], v[150:151] op_sel_hi:[1,0]
	v_pk_mul_f32 v[126:127], v[126:127], v[150:151] op_sel_hi:[1,0]
	v_pk_mul_f32 v[154:155], v[124:125], v[150:151] op_sel_hi:[1,0]
	v_pk_mul_f32 v[124:125], v[122:123], v[150:151] op_sel_hi:[1,0]
	v_cvt_pk_bf16_f32 v122, v126, v127
	v_cvt_pk_bf16_f32 v123, v128, v129
	v_pk_mul_f32 v[120:121], v[120:121], v[150:151] op_sel_hi:[1,0]
	v_cvt_pk_bf16_f32 v124, v124, v125
	v_cvt_pk_bf16_f32 v125, v154, v155
	ds_bpermute_b32 v122, v246, v122
	ds_bpermute_b32 v123, v246, v123
	ds_bpermute_b32 v124, v246, v124
	ds_bpermute_b32 v125, v246, v125
	ds_bpermute_b32 v250, v246, v152
	ds_bpermute_b32 v251, v246, v153
	s_waitcnt lgkmcnt(0)
	global_store_dwordx4 v[250:251], v[122:125], off nt
	v_pk_mul_f32 v[118:119], v[118:119], v[150:151] op_sel_hi:[1,0]
	s_mov_b64 s[44:45], -1
	v_pk_mul_f32 v[122:123], v[116:117], v[150:151] op_sel_hi:[1,0]
	v_pk_mul_f32 v[116:117], v[114:115], v[150:151] op_sel_hi:[1,0]
	v_cvt_pk_bf16_f32 v114, v118, v119
	v_cvt_pk_bf16_f32 v115, v120, v121
	s_nop 0
	v_cvt_pk_bf16_f32 v116, v116, v117
	v_cvt_pk_bf16_f32 v117, v122, v123
	ds_bpermute_b32 v114, v246, v114
	ds_bpermute_b32 v115, v246, v115
	ds_bpermute_b32 v116, v246, v116
	ds_bpermute_b32 v117, v246, v117
	ds_bpermute_b32 v250, v246, v152
	ds_bpermute_b32 v251, v246, v153
	s_waitcnt lgkmcnt(0)
	global_store_dwordx4 v[250:251], v[114:117], off offset:256 nt
	ds_read_b32 v116, v149 offset:64
	s_waitcnt lgkmcnt(0)
	v_pk_mul_f32 v[112:113], v[112:113], v[116:117] op_sel_hi:[1,0]
	v_add_u32_e32 v114, 16, v142
	v_ashrrev_i32_e32 v115, 31, v114
	v_lshlrev_b64 v[114:115], 12, v[114:115]
	v_lshl_add_u64 v[114:115], s[36:37], 0, v[114:115]
	v_lshl_add_u64 v[114:115], v[114:115], 0, v[144:145]
	v_pk_mul_f32 v[110:111], v[110:111], v[116:117] op_sel_hi:[1,0]
	v_pk_mul_f32 v[118:119], v[108:109], v[116:117] op_sel_hi:[1,0]
	v_pk_mul_f32 v[108:109], v[106:107], v[116:117] op_sel_hi:[1,0]
	v_cvt_pk_bf16_f32 v106, v110, v111
	v_cvt_pk_bf16_f32 v107, v112, v113
	v_pk_mul_f32 v[104:105], v[104:105], v[116:117] op_sel_hi:[1,0]
	v_cvt_pk_bf16_f32 v108, v108, v109
	v_cvt_pk_bf16_f32 v109, v118, v119
	ds_bpermute_b32 v106, v246, v106
	ds_bpermute_b32 v107, v246, v107
	ds_bpermute_b32 v108, v246, v108
	ds_bpermute_b32 v109, v246, v109
	ds_bpermute_b32 v250, v246, v114
	ds_bpermute_b32 v251, v246, v115
	s_waitcnt lgkmcnt(0)
	global_store_dwordx4 v[250:251], v[106:109], off nt
	v_pk_mul_f32 v[102:103], v[102:103], v[116:117] op_sel_hi:[1,0]
	s_nop 0
	v_pk_mul_f32 v[106:107], v[100:101], v[116:117] op_sel_hi:[1,0]
	v_pk_mul_f32 v[100:101], v[98:99], v[116:117] op_sel_hi:[1,0]
	v_cvt_pk_bf16_f32 v98, v102, v103
	v_cvt_pk_bf16_f32 v99, v104, v105
	s_nop 0
	v_cvt_pk_bf16_f32 v100, v100, v101
	v_cvt_pk_bf16_f32 v101, v106, v107
	ds_bpermute_b32 v98, v246, v98
	ds_bpermute_b32 v99, v246, v99
	ds_bpermute_b32 v100, v246, v100
	ds_bpermute_b32 v101, v246, v101
	ds_bpermute_b32 v250, v246, v114
	ds_bpermute_b32 v251, v246, v115
	s_waitcnt lgkmcnt(0)
	global_store_dwordx4 v[250:251], v[98:101], off offset:256 nt
	ds_read_b32 v100, v149 offset:128
	s_waitcnt lgkmcnt(0)
	v_pk_mul_f32 v[96:97], v[96:97], v[100:101] op_sel_hi:[1,0]
	v_add_u32_e32 v98, 32, v142
	v_ashrrev_i32_e32 v99, 31, v98
	v_lshlrev_b64 v[98:99], 12, v[98:99]
	v_lshl_add_u64 v[98:99], s[36:37], 0, v[98:99]
	v_lshl_add_u64 v[98:99], v[98:99], 0, v[144:145]
	v_pk_mul_f32 v[94:95], v[94:95], v[100:101] op_sel_hi:[1,0]
	v_pk_mul_f32 v[102:103], v[92:93], v[100:101] op_sel_hi:[1,0]
	v_pk_mul_f32 v[92:93], v[90:91], v[100:101] op_sel_hi:[1,0]
	v_cvt_pk_bf16_f32 v90, v94, v95
	v_cvt_pk_bf16_f32 v91, v96, v97
	v_pk_mul_f32 v[88:89], v[88:89], v[100:101] op_sel_hi:[1,0]
	v_cvt_pk_bf16_f32 v92, v92, v93
	v_cvt_pk_bf16_f32 v93, v102, v103
	ds_bpermute_b32 v90, v246, v90
	ds_bpermute_b32 v91, v246, v91
	ds_bpermute_b32 v92, v246, v92
	ds_bpermute_b32 v93, v246, v93
	ds_bpermute_b32 v250, v246, v98
	ds_bpermute_b32 v251, v246, v99
	s_waitcnt lgkmcnt(0)
	global_store_dwordx4 v[250:251], v[90:93], off nt
	v_pk_mul_f32 v[86:87], v[86:87], v[100:101] op_sel_hi:[1,0]
	s_nop 0
	v_pk_mul_f32 v[90:91], v[84:85], v[100:101] op_sel_hi:[1,0]
	v_pk_mul_f32 v[84:85], v[82:83], v[100:101] op_sel_hi:[1,0]
	v_cvt_pk_bf16_f32 v82, v86, v87
	v_cvt_pk_bf16_f32 v83, v88, v89
	s_nop 0
	v_cvt_pk_bf16_f32 v84, v84, v85
	v_cvt_pk_bf16_f32 v85, v90, v91
	ds_bpermute_b32 v82, v246, v82
	ds_bpermute_b32 v83, v246, v83
	ds_bpermute_b32 v84, v246, v84
	ds_bpermute_b32 v85, v246, v85
	ds_bpermute_b32 v250, v246, v98
	ds_bpermute_b32 v251, v246, v99
	s_waitcnt lgkmcnt(0)
	global_store_dwordx4 v[250:251], v[82:85], off offset:256 nt
	ds_read_b32 v84, v149 offset:192
	s_waitcnt lgkmcnt(0)
; __device__ __forceinline__ unsigned cvt_pk_bf16(float lo, float hi) { unsigned r; asm volatile("v_cvt_pk_bf16_f32 %0, %1, %2" : "=v"(r) : "v"(lo), "v"(hi)); return r; }
;     __device__ __forceinline__ void operator()(const f32x4 (&acc)[2][2][4][2], const Unit& u, int wr, int wc, int fr, int fq) const {
;         asm volatile("" : "+v"(fr), "+v"(fq));
;         const int rl0 = wr * 64 + fr, col0 = u.pn * BM + wc * 32 + 8 * fq;
; #pragma unroll
;         for (int ai = 0; ai < 2; ++ai)
; #pragma unroll
;             for (int m = 0; m < 4; ++m) { const int rl = rl0 + ai * HALF + m * 16; bf16_t* rowp = O + (size_t)(u.pm * BM + rl) * ldc + col0;
;                 const float s = rst[u.idx * BM + rl];
; #pragma unroll
;                 for (int bj = 0; bj < 2; ++bj) { f32x4 v0 = acc[ai][bj][m][0] * s, v1 = acc[ai][bj][m][1] * s;
;                     if (ACT == 1) {
; #pragma unroll
;                         for (int e = 0; e < 4; ++e) { const float a = fmaxf(v0[e], 0.f), b = fmaxf(v1[e], 0.f); v0[e] = a * a; v1[e] = b * b; } }
;                     u32x4 w; w.x = cvt_pk_bf16(v0[0], v0[1]); w.y = cvt_pk_bf16(v0[2], v0[3]); w.z = cvt_pk_bf16(v1[0], v1[1]); w.w = cvt_pk_bf16(v1[2], v1[3]);
;                     __builtin_nontemporal_store(w, (u32x4*)(rowp + bj * HALF)); } }
;     }
	v_pk_mul_f32 v[80:81], v[80:81], v[84:85] op_sel_hi:[1,0]
	v_add_u32_e32 v82, 48, v142
	v_ashrrev_i32_e32 v83, 31, v82
	v_lshlrev_b64 v[82:83], 12, v[82:83]
	v_lshl_add_u64 v[82:83], s[36:37], 0, v[82:83]
	v_lshl_add_u64 v[82:83], v[82:83], 0, v[144:145]
	v_pk_mul_f32 v[78:79], v[78:79], v[84:85] op_sel_hi:[1,0]
	v_pk_mul_f32 v[86:87], v[76:77], v[84:85] op_sel_hi:[1,0]
	v_pk_mul_f32 v[76:77], v[74:75], v[84:85] op_sel_hi:[1,0]
	v_cvt_pk_bf16_f32 v74, v78, v79
	v_cvt_pk_bf16_f32 v75, v80, v81
	v_pk_mul_f32 v[72:73], v[72:73], v[84:85] op_sel_hi:[1,0]
	v_cvt_pk_bf16_f32 v76, v76, v77
	v_cvt_pk_bf16_f32 v77, v86, v87
	ds_bpermute_b32 v74, v246, v74
	ds_bpermute_b32 v75, v246, v75
	ds_bpermute_b32 v76, v246, v76
	ds_bpermute_b32 v77, v246, v77
	ds_bpermute_b32 v250, v246, v82
	ds_bpermute_b32 v251, v246, v83
	s_waitcnt lgkmcnt(0)
	global_store_dwordx4 v[250:251], v[74:77], off nt
	v_pk_mul_f32 v[70:71], v[70:71], v[84:85] op_sel_hi:[1,0]
	s_nop 0
	v_pk_mul_f32 v[74:75], v[68:69], v[84:85] op_sel_hi:[1,0]
	v_pk_mul_f32 v[68:69], v[66:67], v[84:85] op_sel_hi:[1,0]
	v_cvt_pk_bf16_f32 v66, v70, v71
	v_cvt_pk_bf16_f32 v67, v72, v73
	s_nop 0
	v_cvt_pk_bf16_f32 v68, v68, v69
	v_cvt_pk_bf16_f32 v69, v74, v75
	ds_bpermute_b32 v66, v246, v66
	ds_bpermute_b32 v67, v246, v67
	ds_bpermute_b32 v68, v246, v68
	ds_bpermute_b32 v69, v246, v69
	ds_bpermute_b32 v250, v246, v82
	ds_bpermute_b32 v251, v246, v83
	s_waitcnt lgkmcnt(0)
	global_store_dwordx4 v[250:251], v[66:69], off offset:256 nt
	ds_read_b32 v68, v149 offset:512
	s_waitcnt lgkmcnt(0)
	v_pk_mul_f32 v[64:65], v[64:65], v[68:69] op_sel_hi:[1,0]
	v_add_u32_e32 v66, 0x80, v142
	v_ashrrev_i32_e32 v67, 31, v66
	v_lshlrev_b64 v[66:67], 12, v[66:67]
	v_lshl_add_u64 v[66:67], s[36:37], 0, v[66:67]
	v_lshl_add_u64 v[66:67], v[66:67], 0, v[144:145]
	v_pk_mul_f32 v[62:63], v[62:63], v[68:69] op_sel_hi:[1,0]
	v_pk_mul_f32 v[70:71], v[60:61], v[68:69] op_sel_hi:[1,0]
	v_pk_mul_f32 v[60:61], v[58:59], v[68:69] op_sel_hi:[1,0]
	v_cvt_pk_bf16_f32 v58, v62, v63
	v_cvt_pk_bf16_f32 v59, v64, v65
	v_pk_mul_f32 v[56:57], v[56:57], v[68:69] op_sel_hi:[1,0]
	v_cvt_pk_bf16_f32 v60, v60, v61
	v_cvt_pk_bf16_f32 v61, v70, v71
	ds_bpermute_b32 v58, v246, v58
	ds_bpermute_b32 v59, v246, v59
	ds_bpermute_b32 v60, v246, v60
	ds_bpermute_b32 v61, v246, v61
	ds_bpermute_b32 v250, v246, v66
	ds_bpermute_b32 v251, v246, v67
	s_waitcnt lgkmcnt(0)
	global_store_dwordx4 v[250:251], v[58:61], off nt
	v_pk_mul_f32 v[54:55], v[54:55], v[68:69] op_sel_hi:[1,0]
	s_nop 0
	v_pk_mul_f32 v[58:59], v[52:53], v[68:69] op_sel_hi:[1,0]
	v_pk_mul_f32 v[52:53], v[50:51], v[68:69] op_sel_hi:[1,0]
	v_cvt_pk_bf16_f32 v50, v54, v55
	v_cvt_pk_bf16_f32 v51, v56, v57
	s_nop 0
	v_cvt_pk_bf16_f32 v52, v52, v53
	v_cvt_pk_bf16_f32 v53, v58, v59
	ds_bpermute_b32 v50, v246, v50
	ds_bpermute_b32 v51, v246, v51
	ds_bpermute_b32 v52, v246, v52
	ds_bpermute_b32 v53, v246, v53
	ds_bpermute_b32 v250, v246, v66
	ds_bpermute_b32 v251, v246, v67
	s_waitcnt lgkmcnt(0)
	global_store_dwordx4 v[250:251], v[50:53], off offset:256 nt
	ds_read_b32 v52, v149 offset:576
	s_waitcnt lgkmcnt(0)
	v_pk_mul_f32 v[48:49], v[48:49], v[52:53] op_sel_hi:[1,0]
	v_add_u32_e32 v50, 0x90, v142
	v_ashrrev_i32_e32 v51, 31, v50
	v_lshlrev_b64 v[50:51], 12, v[50:51]
	v_lshl_add_u64 v[50:51], s[36:37], 0, v[50:51]
	v_lshl_add_u64 v[50:51], v[50:51], 0, v[144:145]
	v_pk_mul_f32 v[46:47], v[46:47], v[52:53] op_sel_hi:[1,0]
	v_pk_mul_f32 v[54:55], v[44:45], v[52:53] op_sel_hi:[1,0]
	v_pk_mul_f32 v[44:45], v[42:43], v[52:53] op_sel_hi:[1,0]
	v_cvt_pk_bf16_f32 v42, v46, v47
	v_cvt_pk_bf16_f32 v43, v48, v49
	v_pk_mul_f32 v[40:41], v[40:41], v[52:53] op_sel_hi:[1,0]
	v_cvt_pk_bf16_f32 v44, v44, v45
	v_cvt_pk_bf16_f32 v45, v54, v55
	ds_bpermute_b32 v42, v246, v42
	ds_bpermute_b32 v43, v246, v43
	ds_bpermute_b32 v44, v246, v44
	ds_bpermute_b32 v45, v246, v45
	ds_bpermute_b32 v250, v246, v50
	ds_bpermute_b32 v251, v246, v51
	s_waitcnt lgkmcnt(0)
; __device__ __forceinline__ unsigned cvt_pk_bf16(float lo, float hi) { unsigned r; asm volatile("v_cvt_pk_bf16_f32 %0, %1, %2" : "=v"(r) : "v"(lo), "v"(hi)); return r; }
;     __device__ __forceinline__ void operator()(const f32x4 (&acc)[2][2][4][2], const Unit& u, int wr, int wc, int fr, int fq) const {
;         asm volatile("" : "+v"(fr), "+v"(fq));
;         const int rl0 = wr * 64 + fr, col0 = u.pn * BM + wc * 32 + 8 * fq;
; #pragma unroll
;         for (int ai = 0; ai < 2; ++ai)
; #pragma unroll
;             for (int m = 0; m < 4; ++m) { const int rl = rl0 + ai * HALF + m * 16; bf16_t* rowp = O + (size_t)(u.pm * BM + rl) * ldc + col0;
;                 const float s = rst[u.idx * BM + rl];
; #pragma unroll
;                 for (int bj = 0; bj < 2; ++bj) { f32x4 v0 = acc[ai][bj][m][0] * s, v1 = acc[ai][bj][m][1] * s;
;                     if (ACT == 1) {
; #pragma unroll
;                         for (int e = 0; e < 4; ++e) { const float a = fmaxf(v0[e], 0.f), b = fmaxf(v1[e], 0.f); v0[e] = a * a; v1[e] = b * b; } }
;                     u32x4 w; w.x = cvt_pk_bf16(v0[0], v0[1]); w.y = cvt_pk_bf16(v0[2], v0[3]); w.z = cvt_pk_bf16(v1[0], v1[1]); w.w = cvt_pk_bf16(v1[2], v1[3]);
;                     __builtin_nontemporal_store(w, (u32x4*)(rowp + bj * HALF)); } }
;     }
	global_store_dwordx4 v[250:251], v[42:45], off nt
	v_pk_mul_f32 v[38:39], v[38:39], v[52:53] op_sel_hi:[1,0]
	s_nop 0
	v_pk_mul_f32 v[42:43], v[36:37], v[52:53] op_sel_hi:[1,0]
	v_pk_mul_f32 v[36:37], v[34:35], v[52:53] op_sel_hi:[1,0]
	v_cvt_pk_bf16_f32 v34, v38, v39
	v_cvt_pk_bf16_f32 v35, v40, v41
	s_nop 0
	v_cvt_pk_bf16_f32 v36, v36, v37
	v_cvt_pk_bf16_f32 v37, v42, v43
	ds_bpermute_b32 v34, v246, v34
	ds_bpermute_b32 v35, v246, v35
	ds_bpermute_b32 v36, v246, v36
	ds_bpermute_b32 v37, v246, v37
	ds_bpermute_b32 v250, v246, v50
	ds_bpermute_b32 v251, v246, v51
	s_waitcnt lgkmcnt(0)
	global_store_dwordx4 v[250:251], v[34:37], off offset:256 nt
	ds_read_b32 v36, v149 offset:640
	s_waitcnt lgkmcnt(0)
	v_pk_mul_f32 v[32:33], v[32:33], v[36:37] op_sel_hi:[1,0]
	v_add_u32_e32 v34, 0xa0, v142
	v_ashrrev_i32_e32 v35, 31, v34
	v_lshlrev_b64 v[34:35], 12, v[34:35]
	v_lshl_add_u64 v[34:35], s[36:37], 0, v[34:35]
	v_lshl_add_u64 v[34:35], v[34:35], 0, v[144:145]
	v_pk_mul_f32 v[30:31], v[30:31], v[36:37] op_sel_hi:[1,0]
	v_pk_mul_f32 v[38:39], v[28:29], v[36:37] op_sel_hi:[1,0]
	v_pk_mul_f32 v[28:29], v[26:27], v[36:37] op_sel_hi:[1,0]
	v_cvt_pk_bf16_f32 v26, v30, v31
	v_cvt_pk_bf16_f32 v27, v32, v33
	v_pk_mul_f32 v[24:25], v[24:25], v[36:37] op_sel_hi:[1,0]
	v_cvt_pk_bf16_f32 v28, v28, v29
	v_cvt_pk_bf16_f32 v29, v38, v39
	ds_bpermute_b32 v26, v246, v26
	ds_bpermute_b32 v27, v246, v27
	ds_bpermute_b32 v28, v246, v28
	ds_bpermute_b32 v29, v246, v29
	ds_bpermute_b32 v250, v246, v34
	ds_bpermute_b32 v251, v246, v35
	s_waitcnt lgkmcnt(0)
	global_store_dwordx4 v[250:251], v[26:29], off nt
	v_pk_mul_f32 v[22:23], v[22:23], v[36:37] op_sel_hi:[1,0]
	s_nop 0
	v_pk_mul_f32 v[26:27], v[20:21], v[36:37] op_sel_hi:[1,0]
	v_pk_mul_f32 v[20:21], v[18:19], v[36:37] op_sel_hi:[1,0]
	v_cvt_pk_bf16_f32 v18, v22, v23
	v_cvt_pk_bf16_f32 v19, v24, v25
	s_nop 0
	v_cvt_pk_bf16_f32 v20, v20, v21
	v_cvt_pk_bf16_f32 v21, v26, v27
	ds_bpermute_b32 v18, v246, v18
	ds_bpermute_b32 v19, v246, v19
	ds_bpermute_b32 v20, v246, v20
	ds_bpermute_b32 v21, v246, v21
	ds_bpermute_b32 v250, v246, v34
	ds_bpermute_b32 v251, v246, v35
	s_waitcnt lgkmcnt(0)
	global_store_dwordx4 v[250:251], v[18:21], off offset:256 nt
	ds_read_b32 v20, v149 offset:704
	s_waitcnt lgkmcnt(0)
	v_pk_mul_f32 v[16:17], v[16:17], v[20:21] op_sel_hi:[1,0]
	v_add_u32_e32 v18, 0xb0, v142
	v_ashrrev_i32_e32 v19, 31, v18
	v_lshlrev_b64 v[18:19], 12, v[18:19]
	v_lshl_add_u64 v[18:19], s[36:37], 0, v[18:19]
	v_lshl_add_u64 v[18:19], v[18:19], 0, v[144:145]
	v_pk_mul_f32 v[14:15], v[14:15], v[20:21] op_sel_hi:[1,0]
	v_pk_mul_f32 v[22:23], v[12:13], v[20:21] op_sel_hi:[1,0]
	v_pk_mul_f32 v[12:13], v[10:11], v[20:21] op_sel_hi:[1,0]
	v_cvt_pk_bf16_f32 v10, v14, v15
	v_cvt_pk_bf16_f32 v11, v16, v17
	v_pk_mul_f32 v[8:9], v[8:9], v[20:21] op_sel_hi:[1,0]
	v_cvt_pk_bf16_f32 v12, v12, v13
	v_cvt_pk_bf16_f32 v13, v22, v23
	ds_bpermute_b32 v10, v246, v10
	ds_bpermute_b32 v11, v246, v11
	ds_bpermute_b32 v12, v246, v12
	ds_bpermute_b32 v13, v246, v13
	ds_bpermute_b32 v250, v246, v18
	ds_bpermute_b32 v251, v246, v19
	s_waitcnt lgkmcnt(0)
	global_store_dwordx4 v[250:251], v[10:13], off nt
	v_pk_mul_f32 v[6:7], v[6:7], v[20:21] op_sel_hi:[1,0]
	s_nop 0
	v_pk_mul_f32 v[10:11], v[4:5], v[20:21] op_sel_hi:[1,0]
	v_pk_mul_f32 v[4:5], v[2:3], v[20:21] op_sel_hi:[1,0]
	v_cvt_pk_bf16_f32 v2, v6, v7
	v_cvt_pk_bf16_f32 v3, v8, v9
	s_nop 0
	v_cvt_pk_bf16_f32 v4, v4, v5
	v_cvt_pk_bf16_f32 v5, v10, v11
	ds_bpermute_b32 v2, v246, v2
	ds_bpermute_b32 v3, v246, v3
	ds_bpermute_b32 v4, v246, v4
	ds_bpermute_b32 v5, v246, v5
	ds_bpermute_b32 v250, v246, v18
	ds_bpermute_b32 v251, v246, v19
	s_waitcnt lgkmcnt(0)
	global_store_dwordx4 v[250:251], v[2:5], off offset:256 nt
	s_cbranch_vccnz .LBB0_183
	s_andn2_b64 vcc, exec, s[28:29]
	s_cbranch_vccnz .LBB0_182
	s_barrier
	s_branch .LBB0_182

; __device__ __forceinline__ unsigned cvt_pk_bf16(float lo, float hi) { unsigned r; asm volatile("v_cvt_pk_bf16_f32 %0, %1, %2" : "=v"(r) : "v"(lo), "v"(hi)); return r; }
;     __device__ __forceinline__ void operator()(const f32x4 (&acc)[2][2][4][2], const Unit& u, int wr, int wc, int fr, int fq) const {
;         asm volatile("" : "+v"(fr), "+v"(fq));
;         const int rl0 = wr * 64 + fr, col0 = u.pn * BM + wc * 32 + 8 * fq;
; #pragma unroll
;         for (int ai = 0; ai < 2; ++ai)
; #pragma unroll
;             for (int m = 0; m < 4; ++m) { const int rl = rl0 + ai * HALF + m * 16; bf16_t* rowp = O + (size_t)(u.pm * BM + rl) * ldc + col0;
;                 const float s = rst[u.idx * BM + rl];
; #pragma unroll
;                 for (int bj = 0; bj < 2; ++bj) { f32x4 v0 = acc[ai][bj][m][0] * s, v1 = acc[ai][bj][m][1] * s;
;                     if (ACT == 1) {
; #pragma unroll
;                         for (int e = 0; e < 4; ++e) { const float a = fmaxf(v0[e], 0.f), b = fmaxf(v1[e], 0.f); v0[e] = a * a; v1[e] = b * b; } }
;                     u32x4 w; w.x = cvt_pk_bf16(v0[0], v0[1]); w.y = cvt_pk_bf16(v0[2], v0[3]); w.z = cvt_pk_bf16(v1[0], v1[1]); w.w = cvt_pk_bf16(v1[2], v1[3]);
;                     __builtin_nontemporal_store(w, (u32x4*)(rowp + bj * HALF)); } }
;     }
.LBB0_495:
	v_mbcnt_lo_u32_b32 v246, -1, 0
	v_mbcnt_hi_u32_b32 v246, -1, v246
	v_and_b32_e32 v249, 3, v246
	v_lshrrev_b32_e32 v246, 2, v246
	v_lshl_add_u32 v246, v249, 4, v246
	v_lshlrev_b32_e32 v246, 2, v246
	s_lshl_b32 s43, s77, 8
	v_mov_b32_e32 v140, v144
	v_mov_b32_e32 v141, v145
	s_or_b32 s43, s43, s64
	s_andn2_b64 vcc, exec, s[46:47]
	v_lshl_add_u32 v142, v141, 3, s43
	s_lshl_b32 s43, s75, 10
	v_add_u32_e32 v148, s63, v140
	s_add_i32 s43, s43, 0
	v_lshl_add_u32 v140, s76, 8, v148
	v_lshl_add_u32 v148, v148, 2, s43
	v_add_u32_e32 v148, 0x20000, v148
	ds_read_b32 v150, v148
	v_ashrrev_i32_e32 v141, 31, v140
	v_ashrrev_i32_e32 v143, 31, v142
	v_lshlrev_b64 v[152:153], 13, v[140:141]
	v_lshl_add_u64 v[152:153], s[28:29], 0, v[152:153]
	s_waitcnt lgkmcnt(0)
	v_pk_mul_f32 v[122:123], v[122:123], v[150:151] op_sel_hi:[1,0]
	v_pk_mul_f32 v[126:127], v[126:127], v[150:151] op_sel_hi:[1,0]
	v_pk_mul_f32 v[124:125], v[124:125], v[150:151] op_sel_hi:[1,0]
	v_max_f32_e32 v122, 0, v122
	v_pk_mul_f32 v[128:129], v[128:129], v[150:151] op_sel_hi:[1,0]
	v_mul_f32_e32 v141, v122, v122
	v_max_f32_e32 v122, 0, v127
	v_max_f32_e32 v123, 0, v123
	v_max_f32_e32 v124, 0, v124
	v_lshlrev_b64 v[142:143], 1, v[142:143]
	v_max_f32_e32 v126, 0, v126
	v_mul_f32_e32 v122, v122, v122
	v_mul_f32_e32 v127, v123, v123
	v_max_f32_e32 v123, 0, v128
	v_mul_f32_e32 v128, v124, v124
	v_max_f32_e32 v124, 0, v129
	v_max_f32_e32 v125, 0, v125
	v_pk_mul_f32 v[116:117], v[116:117], v[150:151] op_sel_hi:[1,0]
	v_pk_mul_f32 v[114:115], v[114:115], v[150:151] op_sel_hi:[1,0]
	v_lshl_add_u64 v[152:153], v[152:153], 0, v[142:143]
	v_mul_f32_e32 v126, v126, v126
	v_mul_f32_e32 v123, v123, v123
	v_mul_f32_e32 v124, v124, v124
	v_mul_f32_e32 v125, v125, v125
	v_cvt_pk_bf16_f32 v122, v126, v122
	v_pk_mul_f32 v[120:121], v[120:121], v[150:151] op_sel_hi:[1,0]
	v_pk_mul_f32 v[118:119], v[118:119], v[150:151] op_sel_hi:[1,0]
	v_max_f32_e32 v114, 0, v114
	v_max_f32_e32 v115, 0, v115
	v_max_f32_e32 v116, 0, v116
	v_cvt_pk_bf16_f32 v123, v123, v124
	v_cvt_pk_bf16_f32 v124, v141, v127
	v_cvt_pk_bf16_f32 v125, v128, v125
	ds_bpermute_b32 v122, v246, v122
	ds_bpermute_b32 v123, v246, v123
	ds_bpermute_b32 v124, v246, v124
	ds_bpermute_b32 v125, v246, v125
	ds_bpermute_b32 v250, v246, v152
	ds_bpermute_b32 v251, v246, v153
	s_waitcnt lgkmcnt(0)
	global_store_dwordx4 v[250:251], v[122:125], off nt
	v_max_f32_e32 v118, 0, v118
	v_max_f32_e32 v117, 0, v117
	v_mul_f32_e32 v122, v114, v114
	v_max_f32_e32 v114, 0, v119
	v_mul_f32_e32 v119, v115, v115
	v_max_f32_e32 v115, 0, v120
	v_mul_f32_e32 v120, v116, v116
	v_max_f32_e32 v116, 0, v121
	v_mul_f32_e32 v114, v114, v114
	v_mul_f32_e32 v115, v115, v115
	v_mul_f32_e32 v116, v116, v116
	v_mul_f32_e32 v118, v118, v118
	v_mul_f32_e32 v117, v117, v117
	v_cvt_pk_bf16_f32 v114, v118, v114
	v_cvt_pk_bf16_f32 v115, v115, v116
	v_cvt_pk_bf16_f32 v116, v122, v119
	v_cvt_pk_bf16_f32 v117, v120, v117
	ds_bpermute_b32 v114, v246, v114
	ds_bpermute_b32 v115, v246, v115
	ds_bpermute_b32 v116, v246, v116
	ds_bpermute_b32 v117, v246, v117
	ds_bpermute_b32 v250, v246, v152
	ds_bpermute_b32 v251, v246, v153
	s_waitcnt lgkmcnt(0)
	global_store_dwordx4 v[250:251], v[114:117], off offset:256 nt
	ds_read_b32 v116, v148 offset:64
	s_mov_b64 s[46:47], -1
	v_add_u32_e32 v114, 16, v140
	v_ashrrev_i32_e32 v115, 31, v114
	v_lshlrev_b64 v[114:115], 13, v[114:115]
	s_waitcnt lgkmcnt(0)
	v_pk_mul_f32 v[106:107], v[106:107], v[116:117] op_sel_hi:[1,0]
	v_pk_mul_f32 v[110:111], v[110:111], v[116:117] op_sel_hi:[1,0]
	v_pk_mul_f32 v[108:109], v[108:109], v[116:117] op_sel_hi:[1,0]
	v_max_f32_e32 v106, 0, v106
	v_pk_mul_f32 v[112:113], v[112:113], v[116:117] op_sel_hi:[1,0]
	v_mul_f32_e32 v117, v106, v106
	v_max_f32_e32 v106, 0, v111
	v_max_f32_e32 v107, 0, v107
	v_max_f32_e32 v108, 0, v108
	v_lshl_add_u64 v[114:115], s[28:29], 0, v[114:115]
	v_max_f32_e32 v110, 0, v110
	v_mul_f32_e32 v106, v106, v106
	v_mul_f32_e32 v111, v107, v107
	v_max_f32_e32 v107, 0, v112
	v_mul_f32_e32 v112, v108, v108
	v_max_f32_e32 v108, 0, v113
	v_max_f32_e32 v109, 0, v109
	v_pk_mul_f32 v[100:101], v[100:101], v[116:117] op_sel_hi:[1,0]
	v_pk_mul_f32 v[98:99], v[98:99], v[116:117] op_sel_hi:[1,0]
	v_lshl_add_u64 v[114:115], v[114:115], 0, v[142:143]
	v_mul_f32_e32 v110, v110, v110
	v_mul_f32_e32 v107, v107, v107
	v_mul_f32_e32 v108, v108, v108
	v_mul_f32_e32 v109, v109, v109
	v_cvt_pk_bf16_f32 v106, v110, v106
	v_pk_mul_f32 v[104:105], v[104:105], v[116:117] op_sel_hi:[1,0]
	v_pk_mul_f32 v[102:103], v[102:103], v[116:117] op_sel_hi:[1,0]
	v_max_f32_e32 v98, 0, v98
	v_max_f32_e32 v99, 0, v99
	v_max_f32_e32 v100, 0, v100
	v_cvt_pk_bf16_f32 v107, v107, v108
	v_cvt_pk_bf16_f32 v108, v117, v111
	v_cvt_pk_bf16_f32 v109, v112, v109
	ds_bpermute_b32 v106, v246, v106
	ds_bpermute_b32 v107, v246, v107
	ds_bpermute_b32 v108, v246, v108
	ds_bpermute_b32 v109, v246, v109
	ds_bpermute_b32 v250, v246, v114
	ds_bpermute_b32 v251, v246, v115
	s_waitcnt lgkmcnt(0)
	global_store_dwordx4 v[250:251], v[106:109], off nt
	v_max_f32_e32 v102, 0, v102
	v_max_f32_e32 v101, 0, v101
	v_mul_f32_e32 v106, v98, v98
	v_max_f32_e32 v98, 0, v103
	v_mul_f32_e32 v103, v99, v99
	v_max_f32_e32 v99, 0, v104
	v_mul_f32_e32 v104, v100, v100
	v_max_f32_e32 v100, 0, v105
	v_mul_f32_e32 v98, v98, v98
	v_mul_f32_e32 v99, v99, v99
	v_mul_f32_e32 v100, v100, v100
	v_mul_f32_e32 v102, v102, v102
	v_mul_f32_e32 v101, v101, v101
	v_cvt_pk_bf16_f32 v98, v102, v98
	v_cvt_pk_bf16_f32 v99, v99, v100
	v_cvt_pk_bf16_f32 v100, v106, v103
	v_cvt_pk_bf16_f32 v101, v104, v101
	ds_bpermute_b32 v98, v246, v98
	ds_bpermute_b32 v99, v246, v99
	ds_bpermute_b32 v100, v246, v100
	ds_bpermute_b32 v101, v246, v101
	ds_bpermute_b32 v250, v246, v114
	ds_bpermute_b32 v251, v246, v115
	s_waitcnt lgkmcnt(0)
; __device__ __forceinline__ unsigned cvt_pk_bf16(float lo, float hi) { unsigned r; asm volatile("v_cvt_pk_bf16_f32 %0, %1, %2" : "=v"(r) : "v"(lo), "v"(hi)); return r; }
;     __device__ __forceinline__ void operator()(const f32x4 (&acc)[2][2][4][2], const Unit& u, int wr, int wc, int fr, int fq) const {
;         asm volatile("" : "+v"(fr), "+v"(fq));
;         const int rl0 = wr * 64 + fr, col0 = u.pn * BM + wc * 32 + 8 * fq;
; #pragma unroll
;         for (int ai = 0; ai < 2; ++ai)
; #pragma unroll
;             for (int m = 0; m < 4; ++m) { const int rl = rl0 + ai * HALF + m * 16; bf16_t* rowp = O + (size_t)(u.pm * BM + rl) * ldc + col0;
;                 const float s = rst[u.idx * BM + rl];
; #pragma unroll
;                 for (int bj = 0; bj < 2; ++bj) { f32x4 v0 = acc[ai][bj][m][0] * s, v1 = acc[ai][bj][m][1] * s;
;                     if (ACT == 1) {
; #pragma unroll
;                         for (int e = 0; e < 4; ++e) { const float a = fmaxf(v0[e], 0.f), b = fmaxf(v1[e], 0.f); v0[e] = a * a; v1[e] = b * b; } }
;                     u32x4 w; w.x = cvt_pk_bf16(v0[0], v0[1]); w.y = cvt_pk_bf16(v0[2], v0[3]); w.z = cvt_pk_bf16(v1[0], v1[1]); w.w = cvt_pk_bf16(v1[2], v1[3]);
;                     __builtin_nontemporal_store(w, (u32x4*)(rowp + bj * HALF)); } }
;     }
	global_store_dwordx4 v[250:251], v[98:101], off offset:256 nt
	ds_read_b32 v100, v148 offset:128
	s_waitcnt lgkmcnt(0)
	v_pk_mul_f32 v[90:91], v[90:91], v[100:101] op_sel_hi:[1,0]
	v_add_u32_e32 v98, 32, v140
	v_ashrrev_i32_e32 v99, 31, v98
	v_pk_mul_f32 v[94:95], v[94:95], v[100:101] op_sel_hi:[1,0]
	v_pk_mul_f32 v[92:93], v[92:93], v[100:101] op_sel_hi:[1,0]
	v_max_f32_e32 v90, 0, v90
	v_lshlrev_b64 v[98:99], 13, v[98:99]
	v_pk_mul_f32 v[96:97], v[96:97], v[100:101] op_sel_hi:[1,0]
	v_mul_f32_e32 v101, v90, v90
	v_max_f32_e32 v90, 0, v95
	v_max_f32_e32 v91, 0, v91
	v_max_f32_e32 v92, 0, v92
	v_lshl_add_u64 v[98:99], s[28:29], 0, v[98:99]
	v_max_f32_e32 v94, 0, v94
	v_mul_f32_e32 v90, v90, v90
	v_mul_f32_e32 v95, v91, v91
	v_max_f32_e32 v91, 0, v96
	v_mul_f32_e32 v96, v92, v92
	v_max_f32_e32 v92, 0, v97
	v_max_f32_e32 v93, 0, v93
	v_pk_mul_f32 v[84:85], v[84:85], v[100:101] op_sel_hi:[1,0]
	v_pk_mul_f32 v[82:83], v[82:83], v[100:101] op_sel_hi:[1,0]
	v_lshl_add_u64 v[98:99], v[98:99], 0, v[142:143]
	v_mul_f32_e32 v94, v94, v94
	v_mul_f32_e32 v91, v91, v91
	v_mul_f32_e32 v92, v92, v92
	v_mul_f32_e32 v93, v93, v93
	v_cvt_pk_bf16_f32 v90, v94, v90
	v_pk_mul_f32 v[88:89], v[88:89], v[100:101] op_sel_hi:[1,0]
	v_pk_mul_f32 v[86:87], v[86:87], v[100:101] op_sel_hi:[1,0]
	v_max_f32_e32 v82, 0, v82
	v_max_f32_e32 v83, 0, v83
	v_max_f32_e32 v84, 0, v84
	v_cvt_pk_bf16_f32 v91, v91, v92
	v_cvt_pk_bf16_f32 v92, v101, v95
	v_cvt_pk_bf16_f32 v93, v96, v93
	ds_bpermute_b32 v90, v246, v90
	ds_bpermute_b32 v91, v246, v91
	ds_bpermute_b32 v92, v246, v92
	ds_bpermute_b32 v93, v246, v93
	ds_bpermute_b32 v250, v246, v98
	ds_bpermute_b32 v251, v246, v99
	s_waitcnt lgkmcnt(0)
	global_store_dwordx4 v[250:251], v[90:93], off nt
	v_max_f32_e32 v86, 0, v86
	v_max_f32_e32 v85, 0, v85
	v_mul_f32_e32 v90, v82, v82
	v_max_f32_e32 v82, 0, v87
	v_mul_f32_e32 v87, v83, v83
	v_max_f32_e32 v83, 0, v88
	v_mul_f32_e32 v88, v84, v84
	v_max_f32_e32 v84, 0, v89
	v_mul_f32_e32 v82, v82, v82
	v_mul_f32_e32 v83, v83, v83
	v_mul_f32_e32 v84, v84, v84
	v_mul_f32_e32 v86, v86, v86
	v_mul_f32_e32 v85, v85, v85
	v_cvt_pk_bf16_f32 v82, v86, v82
	v_cvt_pk_bf16_f32 v83, v83, v84
	v_cvt_pk_bf16_f32 v84, v90, v87
	v_cvt_pk_bf16_f32 v85, v88, v85
	ds_bpermute_b32 v82, v246, v82
	ds_bpermute_b32 v83, v246, v83
	ds_bpermute_b32 v84, v246, v84
	ds_bpermute_b32 v85, v246, v85
	ds_bpermute_b32 v250, v246, v98
	ds_bpermute_b32 v251, v246, v99
	s_waitcnt lgkmcnt(0)
	global_store_dwordx4 v[250:251], v[82:85], off offset:256 nt
	ds_read_b32 v84, v148 offset:192
	s_waitcnt lgkmcnt(0)
	v_pk_mul_f32 v[74:75], v[74:75], v[84:85] op_sel_hi:[1,0]
	v_add_u32_e32 v82, 48, v140
	v_ashrrev_i32_e32 v83, 31, v82
	v_pk_mul_f32 v[78:79], v[78:79], v[84:85] op_sel_hi:[1,0]
	v_pk_mul_f32 v[76:77], v[76:77], v[84:85] op_sel_hi:[1,0]
	v_max_f32_e32 v74, 0, v74
	v_lshlrev_b64 v[82:83], 13, v[82:83]
	v_pk_mul_f32 v[80:81], v[80:81], v[84:85] op_sel_hi:[1,0]
	v_mul_f32_e32 v85, v74, v74
	v_max_f32_e32 v74, 0, v79
	v_max_f32_e32 v75, 0, v75
	v_max_f32_e32 v76, 0, v76
	v_lshl_add_u64 v[82:83], s[28:29], 0, v[82:83]
	v_max_f32_e32 v78, 0, v78
	v_mul_f32_e32 v74, v74, v74
	v_mul_f32_e32 v79, v75, v75
	v_max_f32_e32 v75, 0, v80
	v_mul_f32_e32 v80, v76, v76
	v_max_f32_e32 v76, 0, v81
	v_max_f32_e32 v77, 0, v77
	v_pk_mul_f32 v[68:69], v[68:69], v[84:85] op_sel_hi:[1,0]
	v_pk_mul_f32 v[66:67], v[66:67], v[84:85] op_sel_hi:[1,0]
	v_lshl_add_u64 v[82:83], v[82:83], 0, v[142:143]
	v_mul_f32_e32 v78, v78, v78
	v_mul_f32_e32 v75, v75, v75
	v_mul_f32_e32 v76, v76, v76
	v_mul_f32_e32 v77, v77, v77
	v_cvt_pk_bf16_f32 v74, v78, v74
	v_pk_mul_f32 v[72:73], v[72:73], v[84:85] op_sel_hi:[1,0]
	v_pk_mul_f32 v[70:71], v[70:71], v[84:85] op_sel_hi:[1,0]
	v_max_f32_e32 v66, 0, v66
	v_max_f32_e32 v67, 0, v67
	v_max_f32_e32 v68, 0, v68
	v_cvt_pk_bf16_f32 v75, v75, v76
	v_cvt_pk_bf16_f32 v76, v85, v79
	v_cvt_pk_bf16_f32 v77, v80, v77
	ds_bpermute_b32 v74, v246, v74
	ds_bpermute_b32 v75, v246, v75
	ds_bpermute_b32 v76, v246, v76
	ds_bpermute_b32 v77, v246, v77
	ds_bpermute_b32 v250, v246, v82
	ds_bpermute_b32 v251, v246, v83
	s_waitcnt lgkmcnt(0)
	global_store_dwordx4 v[250:251], v[74:77], off nt
	v_max_f32_e32 v70, 0, v70
	v_max_f32_e32 v69, 0, v69
	v_mul_f32_e32 v74, v66, v66
	v_max_f32_e32 v66, 0, v71
	v_mul_f32_e32 v71, v67, v67
	v_max_f32_e32 v67, 0, v72
	v_mul_f32_e32 v72, v68, v68
	v_max_f32_e32 v68, 0, v73
	v_mul_f32_e32 v66, v66, v66
	v_mul_f32_e32 v67, v67, v67
	v_mul_f32_e32 v68, v68, v68
	v_mul_f32_e32 v70, v70, v70
	v_mul_f32_e32 v69, v69, v69
	v_cvt_pk_bf16_f32 v66, v70, v66
	v_cvt_pk_bf16_f32 v67, v67, v68
	v_cvt_pk_bf16_f32 v68, v74, v71
	v_cvt_pk_bf16_f32 v69, v72, v69
	ds_bpermute_b32 v66, v246, v66
	ds_bpermute_b32 v67, v246, v67
	ds_bpermute_b32 v68, v246, v68
	ds_bpermute_b32 v69, v246, v69
	ds_bpermute_b32 v250, v246, v82
	ds_bpermute_b32 v251, v246, v83
	s_waitcnt lgkmcnt(0)
	global_store_dwordx4 v[250:251], v[66:69], off offset:256 nt
	ds_read_b32 v68, v148 offset:512
	s_waitcnt lgkmcnt(0)
; __device__ __forceinline__ unsigned cvt_pk_bf16(float lo, float hi) { unsigned r; asm volatile("v_cvt_pk_bf16_f32 %0, %1, %2" : "=v"(r) : "v"(lo), "v"(hi)); return r; }
;     __device__ __forceinline__ void operator()(const f32x4 (&acc)[2][2][4][2], const Unit& u, int wr, int wc, int fr, int fq) const {
;         asm volatile("" : "+v"(fr), "+v"(fq));
;         const int rl0 = wr * 64 + fr, col0 = u.pn * BM + wc * 32 + 8 * fq;
; #pragma unroll
;         for (int ai = 0; ai < 2; ++ai)
; #pragma unroll
;             for (int m = 0; m < 4; ++m) { const int rl = rl0 + ai * HALF + m * 16; bf16_t* rowp = O + (size_t)(u.pm * BM + rl) * ldc + col0;
;                 const float s = rst[u.idx * BM + rl];
; #pragma unroll
;                 for (int bj = 0; bj < 2; ++bj) { f32x4 v0 = acc[ai][bj][m][0] * s, v1 = acc[ai][bj][m][1] * s;
;                     if (ACT == 1) {
; #pragma unroll
;                         for (int e = 0; e < 4; ++e) { const float a = fmaxf(v0[e], 0.f), b = fmaxf(v1[e], 0.f); v0[e] = a * a; v1[e] = b * b; } }
;                     u32x4 w; w.x = cvt_pk_bf16(v0[0], v0[1]); w.y = cvt_pk_bf16(v0[2], v0[3]); w.z = cvt_pk_bf16(v1[0], v1[1]); w.w = cvt_pk_bf16(v1[2], v1[3]);
;                     __builtin_nontemporal_store(w, (u32x4*)(rowp + bj * HALF)); } }
;     }
	v_pk_mul_f32 v[58:59], v[58:59], v[68:69] op_sel_hi:[1,0]
	v_add_u32_e32 v66, 0x80, v140
	v_ashrrev_i32_e32 v67, 31, v66
	v_pk_mul_f32 v[62:63], v[62:63], v[68:69] op_sel_hi:[1,0]
	v_pk_mul_f32 v[60:61], v[60:61], v[68:69] op_sel_hi:[1,0]
	v_max_f32_e32 v58, 0, v58
	v_lshlrev_b64 v[66:67], 13, v[66:67]
	v_pk_mul_f32 v[64:65], v[64:65], v[68:69] op_sel_hi:[1,0]
	v_mul_f32_e32 v69, v58, v58
	v_max_f32_e32 v58, 0, v63
	v_max_f32_e32 v59, 0, v59
	v_max_f32_e32 v60, 0, v60
	v_lshl_add_u64 v[66:67], s[28:29], 0, v[66:67]
	v_max_f32_e32 v62, 0, v62
	v_mul_f32_e32 v58, v58, v58
	v_mul_f32_e32 v63, v59, v59
	v_max_f32_e32 v59, 0, v64
	v_mul_f32_e32 v64, v60, v60
	v_max_f32_e32 v60, 0, v65
	v_max_f32_e32 v61, 0, v61
	v_pk_mul_f32 v[52:53], v[52:53], v[68:69] op_sel_hi:[1,0]
	v_pk_mul_f32 v[50:51], v[50:51], v[68:69] op_sel_hi:[1,0]
	v_lshl_add_u64 v[66:67], v[66:67], 0, v[142:143]
	v_mul_f32_e32 v62, v62, v62
	v_mul_f32_e32 v59, v59, v59
	v_mul_f32_e32 v60, v60, v60
	v_mul_f32_e32 v61, v61, v61
	v_cvt_pk_bf16_f32 v58, v62, v58
	v_pk_mul_f32 v[56:57], v[56:57], v[68:69] op_sel_hi:[1,0]
	v_pk_mul_f32 v[54:55], v[54:55], v[68:69] op_sel_hi:[1,0]
	v_max_f32_e32 v50, 0, v50
	v_max_f32_e32 v51, 0, v51
	v_max_f32_e32 v52, 0, v52
	v_cvt_pk_bf16_f32 v59, v59, v60
	v_cvt_pk_bf16_f32 v60, v69, v63
	v_cvt_pk_bf16_f32 v61, v64, v61
	ds_bpermute_b32 v58, v246, v58
	ds_bpermute_b32 v59, v246, v59
	ds_bpermute_b32 v60, v246, v60
	ds_bpermute_b32 v61, v246, v61
	ds_bpermute_b32 v250, v246, v66
	ds_bpermute_b32 v251, v246, v67
	s_waitcnt lgkmcnt(0)
	global_store_dwordx4 v[250:251], v[58:61], off nt
	v_max_f32_e32 v54, 0, v54
	v_max_f32_e32 v53, 0, v53
	v_mul_f32_e32 v58, v50, v50
	v_max_f32_e32 v50, 0, v55
	v_mul_f32_e32 v55, v51, v51
	v_max_f32_e32 v51, 0, v56
	v_mul_f32_e32 v56, v52, v52
	v_max_f32_e32 v52, 0, v57
	v_mul_f32_e32 v50, v50, v50
	v_mul_f32_e32 v51, v51, v51
	v_mul_f32_e32 v52, v52, v52
	v_mul_f32_e32 v54, v54, v54
	v_mul_f32_e32 v53, v53, v53
	v_cvt_pk_bf16_f32 v50, v54, v50
	v_cvt_pk_bf16_f32 v51, v51, v52
	v_cvt_pk_bf16_f32 v52, v58, v55
	v_cvt_pk_bf16_f32 v53, v56, v53
	ds_bpermute_b32 v50, v246, v50
	ds_bpermute_b32 v51, v246, v51
	ds_bpermute_b32 v52, v246, v52
	ds_bpermute_b32 v53, v246, v53
	ds_bpermute_b32 v250, v246, v66
	ds_bpermute_b32 v251, v246, v67
	s_waitcnt lgkmcnt(0)
	global_store_dwordx4 v[250:251], v[50:53], off offset:256 nt
	ds_read_b32 v52, v148 offset:576
	s_waitcnt lgkmcnt(0)
	v_pk_mul_f32 v[42:43], v[42:43], v[52:53] op_sel_hi:[1,0]
	v_add_u32_e32 v50, 0x90, v140
	v_ashrrev_i32_e32 v51, 31, v50
	v_pk_mul_f32 v[46:47], v[46:47], v[52:53] op_sel_hi:[1,0]
	v_pk_mul_f32 v[44:45], v[44:45], v[52:53] op_sel_hi:[1,0]
	v_max_f32_e32 v42, 0, v42
	v_lshlrev_b64 v[50:51], 13, v[50:51]
	v_pk_mul_f32 v[48:49], v[48:49], v[52:53] op_sel_hi:[1,0]
	v_mul_f32_e32 v53, v42, v42
	v_max_f32_e32 v42, 0, v47
	v_max_f32_e32 v43, 0, v43
	v_max_f32_e32 v44, 0, v44
	v_lshl_add_u64 v[50:51], s[28:29], 0, v[50:51]
	v_max_f32_e32 v46, 0, v46
	v_mul_f32_e32 v42, v42, v42
	v_mul_f32_e32 v47, v43, v43
	v_max_f32_e32 v43, 0, v48
	v_mul_f32_e32 v48, v44, v44
	v_max_f32_e32 v44, 0, v49
	v_max_f32_e32 v45, 0, v45
	v_pk_mul_f32 v[36:37], v[36:37], v[52:53] op_sel_hi:[1,0]
	v_pk_mul_f32 v[34:35], v[34:35], v[52:53] op_sel_hi:[1,0]
	v_lshl_add_u64 v[50:51], v[50:51], 0, v[142:143]
	v_mul_f32_e32 v46, v46, v46
	v_mul_f32_e32 v43, v43, v43
	v_mul_f32_e32 v44, v44, v44
	v_mul_f32_e32 v45, v45, v45
	v_cvt_pk_bf16_f32 v42, v46, v42
	v_pk_mul_f32 v[40:41], v[40:41], v[52:53] op_sel_hi:[1,0]
	v_pk_mul_f32 v[38:39], v[38:39], v[52:53] op_sel_hi:[1,0]
	v_max_f32_e32 v34, 0, v34
	v_max_f32_e32 v35, 0, v35
	v_max_f32_e32 v36, 0, v36
	v_cvt_pk_bf16_f32 v43, v43, v44
	v_cvt_pk_bf16_f32 v44, v53, v47
	v_cvt_pk_bf16_f32 v45, v48, v45
	ds_bpermute_b32 v42, v246, v42
	ds_bpermute_b32 v43, v246, v43
	ds_bpermute_b32 v44, v246, v44
	ds_bpermute_b32 v45, v246, v45
	ds_bpermute_b32 v250, v246, v50
	ds_bpermute_b32 v251, v246, v51
	s_waitcnt lgkmcnt(0)
	global_store_dwordx4 v[250:251], v[42:45], off nt
	v_max_f32_e32 v38, 0, v38
	v_max_f32_e32 v37, 0, v37
	v_mul_f32_e32 v42, v34, v34
	v_max_f32_e32 v34, 0, v39
	v_mul_f32_e32 v39, v35, v35
	v_max_f32_e32 v35, 0, v40
	v_mul_f32_e32 v40, v36, v36
	v_max_f32_e32 v36, 0, v41
	v_mul_f32_e32 v34, v34, v34
	v_mul_f32_e32 v35, v35, v35
	v_mul_f32_e32 v36, v36, v36
	v_mul_f32_e32 v38, v38, v38
	v_mul_f32_e32 v37, v37, v37
	v_cvt_pk_bf16_f32 v34, v38, v34
	v_cvt_pk_bf16_f32 v35, v35, v36
	v_cvt_pk_bf16_f32 v36, v42, v39
	v_cvt_pk_bf16_f32 v37, v40, v37
	ds_bpermute_b32 v34, v246, v34
	ds_bpermute_b32 v35, v246, v35
	ds_bpermute_b32 v36, v246, v36
	ds_bpermute_b32 v37, v246, v37
	ds_bpermute_b32 v250, v246, v50
	ds_bpermute_b32 v251, v246, v51
	s_waitcnt lgkmcnt(0)
	global_store_dwordx4 v[250:251], v[34:37], off offset:256 nt
	ds_read_b32 v36, v148 offset:640
	s_waitcnt lgkmcnt(0)
; __device__ __forceinline__ unsigned cvt_pk_bf16(float lo, float hi) { unsigned r; asm volatile("v_cvt_pk_bf16_f32 %0, %1, %2" : "=v"(r) : "v"(lo), "v"(hi)); return r; }
;     __device__ __forceinline__ void operator()(const f32x4 (&acc)[2][2][4][2], const Unit& u, int wr, int wc, int fr, int fq) const {
;         asm volatile("" : "+v"(fr), "+v"(fq));
;         const int rl0 = wr * 64 + fr, col0 = u.pn * BM + wc * 32 + 8 * fq;
; #pragma unroll
;         for (int ai = 0; ai < 2; ++ai)
; #pragma unroll
;             for (int m = 0; m < 4; ++m) { const int rl = rl0 + ai * HALF + m * 16; bf16_t* rowp = O + (size_t)(u.pm * BM + rl) * ldc + col0;
;                 const float s = rst[u.idx * BM + rl];
; #pragma unroll
;                 for (int bj = 0; bj < 2; ++bj) { f32x4 v0 = acc[ai][bj][m][0] * s, v1 = acc[ai][bj][m][1] * s;
;                     if (ACT == 1) {
; #pragma unroll
;                         for (int e = 0; e < 4; ++e) { const float a = fmaxf(v0[e], 0.f), b = fmaxf(v1[e], 0.f); v0[e] = a * a; v1[e] = b * b; } }
;                     u32x4 w; w.x = cvt_pk_bf16(v0[0], v0[1]); w.y = cvt_pk_bf16(v0[2], v0[3]); w.z = cvt_pk_bf16(v1[0], v1[1]); w.w = cvt_pk_bf16(v1[2], v1[3]);
;                     __builtin_nontemporal_store(w, (u32x4*)(rowp + bj * HALF)); } }
;     }
	v_pk_mul_f32 v[26:27], v[26:27], v[36:37] op_sel_hi:[1,0]
	v_add_u32_e32 v34, 0xa0, v140
	v_ashrrev_i32_e32 v35, 31, v34
	v_pk_mul_f32 v[30:31], v[30:31], v[36:37] op_sel_hi:[1,0]
	v_pk_mul_f32 v[28:29], v[28:29], v[36:37] op_sel_hi:[1,0]
	v_max_f32_e32 v26, 0, v26
	v_lshlrev_b64 v[34:35], 13, v[34:35]
	v_pk_mul_f32 v[32:33], v[32:33], v[36:37] op_sel_hi:[1,0]
	v_mul_f32_e32 v37, v26, v26
	v_max_f32_e32 v26, 0, v31
	v_max_f32_e32 v27, 0, v27
	v_max_f32_e32 v28, 0, v28
	v_lshl_add_u64 v[34:35], s[28:29], 0, v[34:35]
	v_max_f32_e32 v30, 0, v30
	v_mul_f32_e32 v26, v26, v26
	v_mul_f32_e32 v31, v27, v27
	v_max_f32_e32 v27, 0, v32
	v_mul_f32_e32 v32, v28, v28
	v_max_f32_e32 v28, 0, v33
	v_max_f32_e32 v29, 0, v29
	v_pk_mul_f32 v[20:21], v[20:21], v[36:37] op_sel_hi:[1,0]
	v_pk_mul_f32 v[18:19], v[18:19], v[36:37] op_sel_hi:[1,0]
	v_lshl_add_u64 v[34:35], v[34:35], 0, v[142:143]
	v_mul_f32_e32 v30, v30, v30
	v_mul_f32_e32 v27, v27, v27
	v_mul_f32_e32 v28, v28, v28
	v_mul_f32_e32 v29, v29, v29
	v_cvt_pk_bf16_f32 v26, v30, v26
	v_pk_mul_f32 v[24:25], v[24:25], v[36:37] op_sel_hi:[1,0]
	v_pk_mul_f32 v[22:23], v[22:23], v[36:37] op_sel_hi:[1,0]
	v_max_f32_e32 v18, 0, v18
	v_max_f32_e32 v19, 0, v19
	v_max_f32_e32 v20, 0, v20
	v_cvt_pk_bf16_f32 v27, v27, v28
	v_cvt_pk_bf16_f32 v28, v37, v31
	v_cvt_pk_bf16_f32 v29, v32, v29
	ds_bpermute_b32 v26, v246, v26
	ds_bpermute_b32 v27, v246, v27
	ds_bpermute_b32 v28, v246, v28
	ds_bpermute_b32 v29, v246, v29
	ds_bpermute_b32 v250, v246, v34
	ds_bpermute_b32 v251, v246, v35
	s_waitcnt lgkmcnt(0)
	global_store_dwordx4 v[250:251], v[26:29], off nt
	v_max_f32_e32 v22, 0, v22
	v_max_f32_e32 v21, 0, v21
	v_mul_f32_e32 v26, v18, v18
	v_max_f32_e32 v18, 0, v23
	v_mul_f32_e32 v23, v19, v19
	v_max_f32_e32 v19, 0, v24
	v_mul_f32_e32 v24, v20, v20
	v_max_f32_e32 v20, 0, v25
	v_mul_f32_e32 v18, v18, v18
	v_mul_f32_e32 v19, v19, v19
	v_mul_f32_e32 v20, v20, v20
	v_mul_f32_e32 v22, v22, v22
	v_mul_f32_e32 v21, v21, v21
	v_cvt_pk_bf16_f32 v18, v22, v18
	v_cvt_pk_bf16_f32 v19, v19, v20
	v_cvt_pk_bf16_f32 v20, v26, v23
	v_cvt_pk_bf16_f32 v21, v24, v21
	ds_bpermute_b32 v18, v246, v18
	ds_bpermute_b32 v19, v246, v19
	ds_bpermute_b32 v20, v246, v20
	ds_bpermute_b32 v21, v246, v21
	ds_bpermute_b32 v250, v246, v34
	ds_bpermute_b32 v251, v246, v35
	s_waitcnt lgkmcnt(0)
	global_store_dwordx4 v[250:251], v[18:21], off offset:256 nt
	ds_read_b32 v20, v148 offset:704
	s_waitcnt lgkmcnt(0)
	v_pk_mul_f32 v[10:11], v[10:11], v[20:21] op_sel_hi:[1,0]
	v_add_u32_e32 v18, 0xb0, v140
	v_ashrrev_i32_e32 v19, 31, v18
	v_pk_mul_f32 v[14:15], v[14:15], v[20:21] op_sel_hi:[1,0]
	v_pk_mul_f32 v[12:13], v[12:13], v[20:21] op_sel_hi:[1,0]
	v_max_f32_e32 v10, 0, v10
	v_lshlrev_b64 v[18:19], 13, v[18:19]
	v_pk_mul_f32 v[16:17], v[16:17], v[20:21] op_sel_hi:[1,0]
	v_mul_f32_e32 v21, v10, v10
	v_max_f32_e32 v10, 0, v15
	v_max_f32_e32 v11, 0, v11
	v_max_f32_e32 v12, 0, v12
	v_lshl_add_u64 v[18:19], s[28:29], 0, v[18:19]
	v_max_f32_e32 v14, 0, v14
	v_mul_f32_e32 v10, v10, v10
	v_mul_f32_e32 v15, v11, v11
	v_max_f32_e32 v11, 0, v16
	v_mul_f32_e32 v16, v12, v12
	v_max_f32_e32 v12, 0, v17
	v_max_f32_e32 v13, 0, v13
	v_pk_mul_f32 v[4:5], v[4:5], v[20:21] op_sel_hi:[1,0]
	v_pk_mul_f32 v[2:3], v[2:3], v[20:21] op_sel_hi:[1,0]
	v_lshl_add_u64 v[18:19], v[18:19], 0, v[142:143]
	v_mul_f32_e32 v14, v14, v14
	v_mul_f32_e32 v11, v11, v11
	v_mul_f32_e32 v12, v12, v12
	v_mul_f32_e32 v13, v13, v13
	v_cvt_pk_bf16_f32 v10, v14, v10
	v_pk_mul_f32 v[8:9], v[8:9], v[20:21] op_sel_hi:[1,0]
	v_pk_mul_f32 v[6:7], v[6:7], v[20:21] op_sel_hi:[1,0]
	v_max_f32_e32 v2, 0, v2
	v_max_f32_e32 v3, 0, v3
	v_max_f32_e32 v4, 0, v4
	v_cvt_pk_bf16_f32 v11, v11, v12
	v_cvt_pk_bf16_f32 v12, v21, v15
	v_cvt_pk_bf16_f32 v13, v16, v13
	ds_bpermute_b32 v10, v246, v10
	ds_bpermute_b32 v11, v246, v11
	ds_bpermute_b32 v12, v246, v12
	ds_bpermute_b32 v13, v246, v13
	ds_bpermute_b32 v250, v246, v18
	ds_bpermute_b32 v251, v246, v19
	s_waitcnt lgkmcnt(0)
	global_store_dwordx4 v[250:251], v[10:13], off nt
	v_max_f32_e32 v5, 0, v5
	v_max_f32_e32 v6, 0, v6
	v_mul_f32_e32 v10, v2, v2
	v_max_f32_e32 v2, 0, v7
	v_mul_f32_e32 v7, v3, v3
	v_max_f32_e32 v3, 0, v8
	v_mul_f32_e32 v8, v4, v4
	v_max_f32_e32 v4, 0, v9
	v_mul_f32_e32 v2, v2, v2
	v_mul_f32_e32 v3, v3, v3
	v_mul_f32_e32 v4, v4, v4
	v_mul_f32_e32 v5, v5, v5
	v_mul_f32_e32 v6, v6, v6
	v_cvt_pk_bf16_f32 v2, v6, v2
	v_cvt_pk_bf16_f32 v3, v3, v4
	v_cvt_pk_bf16_f32 v4, v10, v7
	v_cvt_pk_bf16_f32 v5, v8, v5
	ds_bpermute_b32 v2, v246, v2
	ds_bpermute_b32 v3, v246, v3
	ds_bpermute_b32 v4, v246, v4
	ds_bpermute_b32 v5, v246, v5
	ds_bpermute_b32 v250, v246, v18
	ds_bpermute_b32 v251, v246, v19
	s_waitcnt lgkmcnt(0)
	global_store_dwordx4 v[250:251], v[2:5], off offset:256 nt
	s_cbranch_vccnz .LBB0_484
	s_andn2_b64 vcc, exec, s[22:23]
	s_cbranch_vccnz .LBB0_483
	s_barrier
	s_branch .LBB0_483
